# non-leader workgroups poll the top-level generation word directly (skip the per-XCD relay hop) on top of the early L1 invalidate
# baseline (speedup 1.0000x reference)
.LBB0_76:
	s_lshl_b64 s[6:7], s[6:7], 2
	s_add_u32 s1, s4, s6
	s_addc_u32 s0, s5, s7
	v_mov_b32_e32 v1, s1
	v_add_co_u32_e32 v4, vcc, 0x1000, v1
	v_mov_b32_e32 v1, s0
	s_nop 0
	v_addc_co_u32_e32 v5, vcc, 0, v1, vcc
	v_mov_b32_e32 v1, 1
	flat_atomic_add v1, v[4:5], v1 offset:1024 sc0
	v_cvt_f32_u32_e32 v3, v2
	v_sub_u32_e32 v4, 0, v2
	v_rcp_iflag_f32_e32 v3, v3
	s_nop 0
	v_mul_f32_e32 v3, 0x4f7ffffe, v3
	v_cvt_u32_f32_e32 v3, v3
	v_mul_lo_u32 v4, v4, v3
	v_mul_hi_u32 v4, v3, v4
	v_add_u32_e32 v3, v3, v4
	s_waitcnt vmcnt(0) lgkmcnt(0)
	v_mul_hi_u32 v3, v1, v3
	v_mul_lo_u32 v5, v3, v2
	v_add_u32_e32 v4, 1, v1
	v_sub_u32_e32 v1, v1, v5
	v_add_u32_e32 v6, 1, v3
	v_cmp_ge_u32_e32 vcc, v1, v2
	v_sub_u32_e32 v5, v1, v2
	s_nop 0
	v_cndmask_b32_e32 v3, v3, v6, vcc
	v_cndmask_b32_e32 v1, v1, v5, vcc
	v_add_u32_e32 v5, 1, v3
	v_cmp_ge_u32_e32 vcc, v1, v2
	s_nop 1
	v_cndmask_b32_e32 v1, v3, v5, vcc
	v_mad_u64_u32 v[2:3], s[6:7], v2, v1, v[2:3]
	v_cmp_ne_u32_e32 vcc, v4, v2
	s_and_saveexec_b64 s[6:7], vcc
	s_xor_b64 s[6:7], exec, s[6:7]
	s_cbranch_execz .LBB0_89
	v_mov_b32_e32 v0, s4
	v_add_co_u32_e32 v2, vcc, 0x3100, v0
	v_mov_b32_e32 v0, s5
	s_nop 0
	v_addc_co_u32_e32 v3, vcc, 0, v0, vcc
	flat_load_dword v0, v[2:3] offset:1024 sc1
	s_add_u32 s14, s4, 0x3500
	s_addc_u32 s15, s5, 0
	s_waitcnt vmcnt(0) lgkmcnt(0)
	v_cmp_eq_u32_e32 vcc, v0, v1
	s_and_saveexec_b64 s[12:13], vcc
	s_cbranch_execz .LBB0_88
	s_mov_b32 s30, 1
	s_mov_b64 s[16:17], 0
	s_branch .LBB0_80

.LBB0_281:
	s_lshl_b32 s0, s76, 2
	s_add_u32 s1, s4, s0
	s_addc_u32 s0, s5, 0
	v_mov_b32_e32 v1, s1
	v_add_co_u32_e32 v4, vcc, 0x1000, v1
	v_mov_b32_e32 v1, s0
	s_nop 0
	v_addc_co_u32_e32 v5, vcc, 0, v1, vcc
	flat_atomic_add v1, v[4:5], v195 offset:1024 sc0
	v_cvt_f32_u32_e32 v3, v2
	v_sub_u32_e32 v4, 0, v2
	v_rcp_iflag_f32_e32 v3, v3
	s_nop 0
	v_mul_f32_e32 v3, 0x4f7ffffe, v3
	v_cvt_u32_f32_e32 v3, v3
	v_mul_lo_u32 v4, v4, v3
	v_mul_hi_u32 v4, v3, v4
	v_add_u32_e32 v3, v3, v4
	s_waitcnt vmcnt(0) lgkmcnt(0)
	v_mul_hi_u32 v3, v1, v3
	v_mul_lo_u32 v5, v3, v2
	v_add_u32_e32 v4, 1, v1
	v_sub_u32_e32 v1, v1, v5
	v_add_u32_e32 v6, 1, v3
	v_sub_u32_e32 v5, v1, v2
	v_cmp_ge_u32_e32 vcc, v1, v2
	s_nop 1
	v_cndmask_b32_e32 v3, v3, v6, vcc
	v_cndmask_b32_e32 v1, v1, v5, vcc
	v_add_u32_e32 v5, 1, v3
	v_cmp_ge_u32_e32 vcc, v1, v2
	s_nop 1
	v_cndmask_b32_e32 v1, v3, v5, vcc
	v_mad_u64_u32 v[2:3], s[6:7], v2, v1, v[2:3]
	v_cmp_ne_u32_e32 vcc, v4, v2
	s_and_saveexec_b64 s[6:7], vcc
	s_xor_b64 s[6:7], exec, s[6:7]
	s_cbranch_execz .LBB0_294
	v_mov_b32_e32 v0, s4
	v_add_co_u32_e32 v2, vcc, 0x3100, v0
	v_mov_b32_e32 v0, s5
	s_nop 0
	v_addc_co_u32_e32 v3, vcc, 0, v0, vcc
	flat_load_dword v0, v[2:3] offset:1024 sc1
	s_add_u32 s12, s4, 0x3500
	s_addc_u32 s13, s5, 0
	s_waitcnt vmcnt(0) lgkmcnt(0)
	v_cmp_eq_u32_e32 vcc, v0, v1
	s_and_saveexec_b64 s[10:11], vcc
	s_cbranch_execz .LBB0_293
	s_mov_b32 s30, 1
	s_mov_b64 s[14:15], 0
	s_branch .LBB0_285

.LBB0_358:
	s_lshl_b32 s0, s76, 2
	s_add_u32 s1, s4, s0
	s_addc_u32 s0, s5, 0
	v_mov_b32_e32 v1, s1
	v_add_co_u32_e32 v4, vcc, 0x1000, v1
	v_mov_b32_e32 v1, s0
	s_nop 0
	v_addc_co_u32_e32 v5, vcc, 0, v1, vcc
	flat_atomic_add v1, v[4:5], v195 offset:1024 sc0
	v_cvt_f32_u32_e32 v3, v2
	v_sub_u32_e32 v4, 0, v2
	v_rcp_iflag_f32_e32 v3, v3
	s_nop 0
	v_mul_f32_e32 v3, 0x4f7ffffe, v3
	v_cvt_u32_f32_e32 v3, v3
	v_mul_lo_u32 v4, v4, v3
	v_mul_hi_u32 v4, v3, v4
	v_add_u32_e32 v3, v3, v4
	s_waitcnt vmcnt(0) lgkmcnt(0)
	v_mul_hi_u32 v3, v1, v3
	v_mul_lo_u32 v5, v3, v2
	v_add_u32_e32 v4, 1, v1
	v_sub_u32_e32 v1, v1, v5
	v_add_u32_e32 v6, 1, v3
	v_sub_u32_e32 v5, v1, v2
	v_cmp_ge_u32_e32 vcc, v1, v2
	s_nop 1
	v_cndmask_b32_e32 v3, v3, v6, vcc
	v_cndmask_b32_e32 v1, v1, v5, vcc
	v_add_u32_e32 v5, 1, v3
	v_cmp_ge_u32_e32 vcc, v1, v2
	s_nop 1
	v_cndmask_b32_e32 v1, v3, v5, vcc
	v_mad_u64_u32 v[2:3], s[6:7], v2, v1, v[2:3]
	v_cmp_ne_u32_e32 vcc, v4, v2
	s_and_saveexec_b64 s[6:7], vcc
	s_xor_b64 s[6:7], exec, s[6:7]
	s_cbranch_execz .LBB0_371
	v_mov_b32_e32 v0, s4
	v_add_co_u32_e32 v2, vcc, 0x3100, v0
	v_mov_b32_e32 v0, s5
	s_nop 0
	v_addc_co_u32_e32 v3, vcc, 0, v0, vcc
	flat_load_dword v0, v[2:3] offset:1024 sc1
	s_add_u32 s12, s4, 0x3500
	s_addc_u32 s13, s5, 0
	s_waitcnt vmcnt(0) lgkmcnt(0)
	v_cmp_eq_u32_e32 vcc, v0, v1
	s_and_saveexec_b64 s[10:11], vcc
	s_cbranch_execz .LBB0_370
	s_mov_b32 s8, 1
	s_mov_b64 s[14:15], 0
	s_branch .LBB0_362

.LBB0_519:
	s_lshl_b32 s0, s76, 2
	s_add_u32 s1, s4, s0
	s_addc_u32 s0, s5, 0
	v_mov_b32_e32 v1, s1
	v_add_co_u32_e32 v4, vcc, 0x1000, v1
	v_mov_b32_e32 v1, s0
	s_nop 0
	v_addc_co_u32_e32 v5, vcc, 0, v1, vcc
	flat_atomic_add v3, v[4:5], v195 offset:1024 sc0
	v_cvt_f32_u32_e32 v1, v2
	v_sub_u32_e32 v4, 0, v2
	v_rcp_iflag_f32_e32 v1, v1
	s_nop 0
	v_mul_f32_e32 v1, 0x4f7ffffe, v1
	v_cvt_u32_f32_e32 v1, v1
	v_mul_lo_u32 v4, v4, v1
	v_mul_hi_u32 v4, v1, v4
	v_add_u32_e32 v1, v1, v4
	s_waitcnt vmcnt(0) lgkmcnt(0)
	v_mul_hi_u32 v1, v3, v1
	v_mul_lo_u32 v4, v1, v2
	v_sub_u32_e32 v4, v3, v4
	v_cmp_ge_u32_e32 vcc, v4, v2
	v_add_u32_e32 v5, 1, v1
	s_nop 0
	v_cndmask_b32_e32 v1, v1, v5, vcc
	v_sub_u32_e32 v5, v4, v2
	v_cndmask_b32_e32 v4, v4, v5, vcc
	v_cmp_ge_u32_e32 vcc, v4, v2
	v_add_u32_e32 v4, 1, v1
	s_nop 0
	v_cndmask_b32_e32 v1, v1, v4, vcc
	v_add_u32_e32 v4, 1, v3
	v_mad_u64_u32 v[2:3], s[6:7], v2, v1, v[2:3]
	v_cmp_ne_u32_e32 vcc, v4, v2
	s_and_saveexec_b64 s[6:7], vcc
	s_xor_b64 s[6:7], exec, s[6:7]
	s_cbranch_execz .LBB0_532
	v_mov_b32_e32 v0, s4
	v_add_co_u32_e32 v2, vcc, 0x3100, v0
	v_mov_b32_e32 v0, s5
	s_nop 0
	v_addc_co_u32_e32 v3, vcc, 0, v0, vcc
	flat_load_dword v0, v[2:3] offset:1024 sc1
	s_add_u32 s12, s4, 0x3500
	s_addc_u32 s13, s5, 0
	s_waitcnt vmcnt(0) lgkmcnt(0)
	v_cmp_eq_u32_e32 vcc, v0, v1
	s_and_saveexec_b64 s[10:11], vcc
	s_cbranch_execz .LBB0_531
	s_mov_b32 s8, 1
	s_mov_b64 s[16:17], 0
	s_branch .LBB0_523

.LBB0_875:
	s_lshl_b32 s0, s76, 2
	s_add_u32 s1, s4, s0
	s_addc_u32 s0, s5, 0
	v_mov_b32_e32 v1, s1
	v_add_co_u32_e32 v4, vcc, 0x1000, v1
	v_mov_b32_e32 v1, s0
	s_nop 0
	v_addc_co_u32_e32 v5, vcc, 0, v1, vcc
	flat_atomic_add v3, v[4:5], v195 offset:1024 sc0
	v_cvt_f32_u32_e32 v1, v2
	v_sub_u32_e32 v4, 0, v2
	v_rcp_iflag_f32_e32 v1, v1
	s_nop 0
	v_mul_f32_e32 v1, 0x4f7ffffe, v1
	v_cvt_u32_f32_e32 v1, v1
	v_mul_lo_u32 v4, v4, v1
	v_mul_hi_u32 v4, v1, v4
	v_add_u32_e32 v1, v1, v4
	s_waitcnt vmcnt(0) lgkmcnt(0)
	v_mul_hi_u32 v1, v3, v1
	v_mul_lo_u32 v4, v1, v2
	v_sub_u32_e32 v4, v3, v4
	v_cmp_ge_u32_e32 vcc, v4, v2
	v_add_u32_e32 v5, 1, v1
	s_nop 0
	v_cndmask_b32_e32 v1, v1, v5, vcc
	v_sub_u32_e32 v5, v4, v2
	v_cndmask_b32_e32 v4, v4, v5, vcc
	v_cmp_ge_u32_e32 vcc, v4, v2
	v_add_u32_e32 v4, 1, v1
	s_nop 0
	v_cndmask_b32_e32 v1, v1, v4, vcc
	v_add_u32_e32 v4, 1, v3
	v_mad_u64_u32 v[2:3], s[6:7], v2, v1, v[2:3]
	v_cmp_ne_u32_e32 vcc, v4, v2
	s_and_saveexec_b64 s[6:7], vcc
	s_xor_b64 s[6:7], exec, s[6:7]
	s_cbranch_execz .LBB0_888
	v_mov_b32_e32 v0, s4
	v_add_co_u32_e32 v2, vcc, 0x3100, v0
	v_mov_b32_e32 v0, s5
	s_nop 0
	v_addc_co_u32_e32 v3, vcc, 0, v0, vcc
	flat_load_dword v0, v[2:3] offset:1024 sc1
	s_add_u32 s12, s4, 0x3500
	s_addc_u32 s13, s5, 0
	s_waitcnt vmcnt(0) lgkmcnt(0)
	v_cmp_eq_u32_e32 vcc, v0, v1
	s_and_saveexec_b64 s[10:11], vcc
	s_cbranch_execz .LBB0_887
	s_mov_b32 s8, 1
	s_mov_b64 s[14:15], 0
	s_branch .LBB0_879

.LBB0_948:
	s_lshl_b32 s1, s76, 2
	s_add_u32 s9, s4, s1
	s_addc_u32 s1, s5, 0
	v_mov_b32_e32 v1, s9
	v_add_co_u32_e32 v4, vcc, 0x1000, v1
	v_mov_b32_e32 v1, s1
	s_nop 0
	v_addc_co_u32_e32 v5, vcc, 0, v1, vcc
	flat_atomic_add v1, v[4:5], v195 offset:1024 sc0
	v_cvt_f32_u32_e32 v3, v2
	v_sub_u32_e32 v4, 0, v2
	v_rcp_iflag_f32_e32 v3, v3
	s_nop 0
	v_mul_f32_e32 v3, 0x4f7ffffe, v3
	v_cvt_u32_f32_e32 v3, v3
	v_mul_lo_u32 v4, v4, v3
	v_mul_hi_u32 v4, v3, v4
	v_add_u32_e32 v3, v3, v4
	s_waitcnt vmcnt(0) lgkmcnt(0)
	v_mul_hi_u32 v3, v1, v3
	v_mul_lo_u32 v5, v3, v2
	v_add_u32_e32 v4, 1, v1
	v_sub_u32_e32 v1, v1, v5
	v_add_u32_e32 v6, 1, v3
	v_sub_u32_e32 v5, v1, v2
	v_cmp_ge_u32_e32 vcc, v1, v2
	s_nop 1
	v_cndmask_b32_e32 v3, v3, v6, vcc
	v_cndmask_b32_e32 v1, v1, v5, vcc
	v_add_u32_e32 v5, 1, v3
	v_cmp_ge_u32_e32 vcc, v1, v2
	s_nop 1
	v_cndmask_b32_e32 v1, v3, v5, vcc
	v_mad_u64_u32 v[2:3], s[10:11], v2, v1, v[2:3]
	v_cmp_ne_u32_e32 vcc, v4, v2
	s_and_saveexec_b64 s[10:11], vcc
	s_xor_b64 s[10:11], exec, s[10:11]
	s_cbranch_execz .LBB0_961
	v_mov_b32_e32 v0, s4
	v_add_co_u32_e32 v2, vcc, 0x3100, v0
	v_mov_b32_e32 v0, s5
	s_nop 0
	v_addc_co_u32_e32 v3, vcc, 0, v0, vcc
	flat_load_dword v0, v[2:3] offset:1024 sc1
	s_add_u32 s14, s4, 0x3500
	s_addc_u32 s15, s5, 0
	s_waitcnt vmcnt(0) lgkmcnt(0)
	v_cmp_eq_u32_e32 vcc, v0, v1
	s_and_saveexec_b64 s[12:13], vcc
	s_cbranch_execz .LBB0_960
	s_mov_b32 s29, 1
	s_mov_b64 s[16:17], 0
	s_branch .LBB0_952

.LBB0_999:
	s_lshl_b32 s0, s76, 2
	s_add_u32 s1, s10, s0
	s_addc_u32 s0, s11, 0
	v_mov_b32_e32 v1, s1
	v_add_co_u32_e32 v4, vcc, 0x1000, v1
	v_mov_b32_e32 v1, s0
	s_nop 0
	v_addc_co_u32_e32 v5, vcc, 0, v1, vcc
	flat_atomic_add v1, v[4:5], v195 offset:1024 sc0
	v_cvt_f32_u32_e32 v3, v2
	v_sub_u32_e32 v4, 0, v2
	v_rcp_iflag_f32_e32 v3, v3
	s_nop 0
	v_mul_f32_e32 v3, 0x4f7ffffe, v3
	v_cvt_u32_f32_e32 v3, v3
	v_mul_lo_u32 v4, v4, v3
	v_mul_hi_u32 v4, v3, v4
	v_add_u32_e32 v3, v3, v4
	s_waitcnt vmcnt(0) lgkmcnt(0)
	v_mul_hi_u32 v3, v1, v3
	v_mul_lo_u32 v5, v3, v2
	v_add_u32_e32 v4, 1, v1
	v_sub_u32_e32 v1, v1, v5
	v_add_u32_e32 v6, 1, v3
	v_sub_u32_e32 v5, v1, v2
	v_cmp_ge_u32_e32 vcc, v1, v2
	s_nop 1
	v_cndmask_b32_e32 v3, v3, v6, vcc
	v_cndmask_b32_e32 v1, v1, v5, vcc
	v_add_u32_e32 v5, 1, v3
	v_cmp_ge_u32_e32 vcc, v1, v2
	s_nop 1
	v_cndmask_b32_e32 v1, v3, v5, vcc
	v_mad_u64_u32 v[2:3], s[8:9], v2, v1, v[2:3]
	v_cmp_ne_u32_e32 vcc, v4, v2
	s_and_saveexec_b64 s[8:9], vcc
	s_xor_b64 s[12:13], exec, s[8:9]
	s_cbranch_execz .LBB0_1012
	v_mov_b32_e32 v0, s10
	v_add_co_u32_e32 v2, vcc, 0x3100, v0
	v_mov_b32_e32 v0, s11
	s_nop 0
	v_addc_co_u32_e32 v3, vcc, 0, v0, vcc
	flat_load_dword v0, v[2:3] offset:1024 sc1
	s_add_u32 s16, s10, 0x3500
	s_addc_u32 s17, s11, 0
	s_waitcnt vmcnt(0) lgkmcnt(0)
	v_cmp_eq_u32_e32 vcc, v0, v1
	s_and_saveexec_b64 s[14:15], vcc
	s_cbranch_execz .LBB0_1011
	s_mov_b32 s8, 1
	s_mov_b64 s[18:19], 0
	s_branch .LBB0_1003
